# grid barrier: non-leader workgroups issue their L1 invalidate right after arrival (before polling) instead of after release; leader unchanged
# speedup vs baseline: 1.0324x; 1.0092x over previous
.LBB0_169:
	s_or_b64 exec, exec, s[6:7]
	v_cvt_f32_u32_e32 v4, v2
	s_waitcnt vmcnt(0)
	v_readfirstlane_b32 s4, v3
	v_sub_u32_e32 v3, 0, v2
	v_rcp_iflag_f32_e32 v4, v4
	v_add_u32_e32 v5, s4, v1
	v_mul_f32_e32 v4, 0x4f7ffffe, v4
	v_cvt_u32_f32_e32 v4, v4
	v_mul_lo_u32 v1, v3, v4
	v_mul_hi_u32 v1, v4, v1
	v_add_u32_e32 v1, v4, v1
	v_mul_hi_u32 v1, v5, v1
	v_mul_lo_u32 v3, v1, v2
	v_sub_u32_e32 v3, v5, v3
	v_add_u32_e32 v4, 1, v1
	v_cmp_ge_u32_e32 vcc, v3, v2
	s_nop 1
	v_cndmask_b32_e32 v1, v1, v4, vcc
	v_sub_u32_e32 v4, v3, v2
	v_cndmask_b32_e32 v3, v3, v4, vcc
	v_add_u32_e32 v4, 1, v1
	v_cmp_ge_u32_e32 vcc, v3, v2
	v_add_u32_e32 v3, 1, v5
	s_nop 0
	v_cndmask_b32_e32 v1, v1, v4, vcc
	v_mul_lo_u32 v4, v2, v1
	v_add_u32_e32 v2, v4, v2
	v_cmp_ne_u32_e32 vcc, v3, v2
	s_and_saveexec_b64 s[4:5], vcc
	s_xor_b64 s[4:5], exec, s[4:5]
	s_cbranch_execz .LBB0_183
	s_waitcnt lgkmcnt(0)
	v_mov_b32_e32 v0, 0x2000
	buffer_inv sc1
	global_load_dword v0, v0, s[2:3] offset:1024 sc1
	s_add_u32 s10, s2, 0x2400
	s_addc_u32 s11, s3, 0
	s_waitcnt vmcnt(0)
	v_cmp_eq_u32_e32 vcc, v0, v1
	s_and_saveexec_b64 s[6:7], vcc
	s_cbranch_execz .LBB0_182
	s_add_u32 s8, s28, 0xee48200
	s_addc_u32 s9, s29, 0
	s_mov_b32 s17, 1
	s_mov_b64 s[12:13], 0
	v_mov_b32_e32 v0, 0
	s_branch .LBB0_173

.LBB0_182:
	s_or_b64 exec, exec, s[6:7]
	s_waitcnt vmcnt(0)

	s_waitcnt vmcnt(0)

.LBB0_254:
	s_or_b64 exec, exec, s[6:7]
	v_cvt_f32_u32_e32 v5, v3
	s_waitcnt vmcnt(0)
	v_readfirstlane_b32 s4, v4
	v_sub_u32_e32 v4, 0, v3
	v_rcp_iflag_f32_e32 v5, v5
	v_add_u32_e32 v6, s4, v0
	v_mul_f32_e32 v5, 0x4f7ffffe, v5
	v_cvt_u32_f32_e32 v5, v5
	v_mul_lo_u32 v0, v4, v5
	v_mul_hi_u32 v0, v5, v0
	v_add_u32_e32 v0, v5, v0
	v_mul_hi_u32 v0, v6, v0
	v_mul_lo_u32 v4, v0, v3
	v_sub_u32_e32 v4, v6, v4
	v_add_u32_e32 v5, 1, v0
	v_cmp_ge_u32_e32 vcc, v4, v3
	s_nop 1
	v_cndmask_b32_e32 v0, v0, v5, vcc
	v_sub_u32_e32 v5, v4, v3
	v_cndmask_b32_e32 v4, v4, v5, vcc
	v_add_u32_e32 v5, 1, v0
	v_cmp_ge_u32_e32 vcc, v4, v3
	v_add_u32_e32 v4, 1, v6
	s_nop 0
	v_cndmask_b32_e32 v0, v0, v5, vcc
	v_mul_lo_u32 v5, v3, v0
	v_add_u32_e32 v3, v5, v3
	v_cmp_ne_u32_e32 vcc, v4, v3
	s_and_saveexec_b64 s[4:5], vcc
	s_xor_b64 s[4:5], exec, s[4:5]
	s_cbranch_execz .LBB0_268
	s_waitcnt lgkmcnt(0)
	buffer_inv sc1
	global_load_dword v2, v196, s[2:3] offset:1024 sc1
	s_add_u32 s18, s2, 0x2400
	s_addc_u32 s19, s3, 0
	s_waitcnt vmcnt(0)
	v_cmp_eq_u32_e32 vcc, v2, v0
	s_and_saveexec_b64 s[6:7], vcc
	s_cbranch_execz .LBB0_267
	s_mov_b32 s14, 1
	s_mov_b64 s[52:53], 0
	s_branch .LBB0_258

.LBB0_1004:
	s_or_b64 exec, exec, s[18:19]
	v_cvt_f32_u32_e32 v5, v3
	s_waitcnt vmcnt(0)
	v_readfirstlane_b32 s4, v4
	v_sub_u32_e32 v4, 0, v3
	v_rcp_iflag_f32_e32 v5, v5
	v_add_u32_e32 v6, s4, v0
	v_mul_f32_e32 v5, 0x4f7ffffe, v5
	v_cvt_u32_f32_e32 v5, v5
	v_mul_lo_u32 v0, v4, v5
	v_mul_hi_u32 v0, v5, v0
	v_add_u32_e32 v0, v5, v0
	v_mul_hi_u32 v0, v6, v0
	v_mul_lo_u32 v4, v0, v3
	v_sub_u32_e32 v4, v6, v4
	v_add_u32_e32 v5, 1, v0
	v_cmp_ge_u32_e32 vcc, v4, v3
	s_nop 1
	v_cndmask_b32_e32 v0, v0, v5, vcc
	v_sub_u32_e32 v5, v4, v3
	v_cndmask_b32_e32 v4, v4, v5, vcc
	v_add_u32_e32 v5, 1, v0
	v_cmp_ge_u32_e32 vcc, v4, v3
	v_add_u32_e32 v4, 1, v6
	s_nop 0
	v_cndmask_b32_e32 v0, v0, v5, vcc
	v_mul_lo_u32 v5, v3, v0
	v_add_u32_e32 v3, v5, v3
	v_cmp_ne_u32_e32 vcc, v4, v3
	s_and_saveexec_b64 s[4:5], vcc
	s_xor_b64 s[4:5], exec, s[4:5]
	s_cbranch_execz .LBB0_1018
	s_waitcnt lgkmcnt(0)
	buffer_inv sc1
	global_load_dword v2, v196, s[2:3] offset:1024 sc1
	s_add_u32 s52, s2, 0x2400
	s_addc_u32 s53, s3, 0
	s_waitcnt vmcnt(0)
	v_cmp_eq_u32_e32 vcc, v2, v0
	s_and_saveexec_b64 s[18:19], vcc
	s_cbranch_execz .LBB0_1017
	s_mov_b32 s14, 1
	s_mov_b64 s[54:55], 0
	s_branch .LBB0_1008

.LBB0_1017:
	s_or_b64 exec, exec, s[18:19]
	s_waitcnt vmcnt(0)

	s_waitcnt vmcnt(0)
